# conv item tail loads hoisted, hot loops kept at the previous version's code alignment (dead padding after unconditional branches)
# speedup vs baseline: 1.0031x; 1.0031x over previous
; __device__ __forceinline__ void dn_conv_token4(const P& p, int m0, int lane) {
;     const bf16_t* PRE = (const bf16_t*)(p.ws + WS_DNPRE);
;     int s0, s1;
;     if (m0 < MLAT) { s0 = m0 & ~2047; s1 = s0 + 2048; } else { s0 = MLAT + ((m0 - MLAT) & ~255); s1 = s0 + 256; }
; #pragma unroll 1
;     for (int cgp = 0; cgp < 3; ++cgp) {
;         const int col = cgp * 512 + lane * 8;
;         f32x4 w[5][2];
; #pragma unroll
;         for (int j = 0; j < 5; ++j) { w[j][0] = *(const f32x4*)(p.conv_w + j * 1536 + col); w[j][1] = *(const f32x4*)(p.conv_w + j * 1536 + col + 4); }
;         u32x4 xr[8];
; #pragma unroll
;         for (int r = 0; r < 8; ++r) { const int mm = m0 + r - 2; xr[r] = (mm >= s0 && mm < s1) ? *(const u32x4*)(PRE + (size_t)mm * 1536 + col) : (u32x4){0u, 0u, 0u, 0u}; }
;     ...
;         const int m = m0 + (lane >> 4), idx = lane & 15;
;         const float a = ((const float*)(p.ws + WS_AB))[(size_t)m * 16 + idx];
.LBB0_491:
	s_mul_i32 s9, s91, 0xc00
	s_mul_hi_i32 s8, s91, 0xc00
	s_add_u32 s12, s89, s9
	s_addc_u32 s13, s90, s8
	s_mul_i32 s9, s92, 0xc00
	s_mul_hi_i32 s8, s92, 0xc00
	s_add_u32 s14, s89, s9
	s_addc_u32 s15, s90, s8
	s_mul_i32 s9, s93, 0xc00
	s_mul_hi_i32 s8, s93, 0xc00
	s_add_u32 s20, s89, s9
	s_addc_u32 s21, s90, s8
	s_mul_i32 s9, s94, 0xc00
	s_mul_hi_i32 s8, s94, 0xc00
	s_add_u32 s22, s89, s9
	s_addc_u32 s23, s90, s8
	s_add_i32 s8, s95, s88
	s_lshl_b32 s24, s8, 2
	v_or_b32_e32 v124, s24, v108
	v_ashrrev_i32_e32 v125, 31, v124
	v_lshlrev_b64 v[124:125], 4, v[124:125]
	v_or_b32_e32 v124, v124, v109
	v_lshl_add_u64 v[126:127], v[124:125], 2, s[16:17]
	global_load_dword v128, v[126:127], off
	s_and_b32 s9, s24, 0xfffff800
	s_and_b32 s11, s24, 0x7fffff00
	s_add_i32 s10, s9, 0x800
	s_add_i32 s25, s11, 0x100
	s_cmpk_lt_i32 s8, 0x1000
	s_cselect_b32 s48, s10, s25
	s_cselect_b32 s49, s9, s11
	s_add_i32 s10, s24, -2
	s_cmp_ge_i32 s10, s49
	s_cselect_b64 s[8:9], -1, 0
	s_cmp_lt_i32 s10, s48
	s_cselect_b64 s[10:11], -1, 0
	s_and_b64 s[26:27], s[8:9], s[10:11]
	s_add_i32 s10, s24, -1
	s_cmp_ge_i32 s10, s49
	s_cselect_b64 s[8:9], -1, 0
	s_cmp_lt_i32 s10, s48
	s_cselect_b64 s[10:11], -1, 0
	s_and_b64 s[28:29], s[8:9], s[10:11]
	s_cmp_ge_i32 s24, s49
	s_cselect_b64 s[8:9], -1, 0
	s_cmp_lt_i32 s24, s48
	s_cselect_b64 s[10:11], -1, 0
	s_and_b64 s[30:31], s[8:9], s[10:11]
	s_ashr_i32 s25, s24, 31
	s_or_b32 s8, s24, 1
	s_cmp_ge_i32 s8, s49
	s_cselect_b64 s[10:11], -1, 0
	s_cmp_lt_i32 s8, s48
	s_cselect_b64 s[34:35], -1, 0
	s_and_b64 s[34:35], s[10:11], s[34:35]
	s_ashr_i32 s9, s8, 31
	s_or_b32 s10, s24, 2
	s_cmp_ge_i32 s10, s49
	s_cselect_b64 s[40:41], -1, 0
	s_cmp_lt_i32 s10, s48
	s_cselect_b64 s[42:43], -1, 0
	s_and_b64 s[40:41], s[40:41], s[42:43]
	s_ashr_i32 s11, s10, 31
	s_or_b32 s72, s24, 3
	s_cmp_ge_i32 s72, s49
	s_cselect_b64 s[42:43], -1, 0
	s_cmp_lt_i32 s72, s48
	s_cselect_b64 s[44:45], -1, 0
	s_and_b64 s[42:43], s[42:43], s[44:45]
	s_ashr_i32 s73, s72, 31
	s_add_i32 s46, s24, 4
	s_cmp_ge_i32 s46, s49
	s_cselect_b64 s[44:45], -1, 0
	s_cmp_lt_i32 s46, s48
	s_cselect_b64 s[46:47], -1, 0
	s_and_b64 s[44:45], s[44:45], s[46:47]
	s_add_i32 s50, s24, 5
	s_cmp_ge_i32 s50, s49
	s_cselect_b64 s[46:47], -1, 0
	s_cmp_lt_i32 s50, s48
	s_cselect_b64 s[48:49], -1, 0
	s_and_b64 s[46:47], s[46:47], s[48:49]
	s_lshl_b64 s[48:49], s[24:25], 10
	s_lshl_b64 s[76:77], s[8:9], 10
	s_lshl_b64 s[80:81], s[10:11], 10
	s_lshl_b64 s[82:83], s[72:73], 10
	s_mov_b64 s[84:85], 0
	s_mov_b64 s[86:87], s[2:3]
	s_branch .LBB0_493
	s_nop 0
	s_nop 0
	s_nop 0
	s_nop 0
	s_nop 0
	s_nop 0
	s_nop 0
	s_nop 0
	s_nop 0
	s_nop 0
	s_nop 0
	s_nop 0
	s_nop 0

; __device__ __forceinline__ void dn_prep_task(const P& p, int task, unsigned char* sm, int tid) {
;     const int h = task & 3, bc = task >> 2, ck = bc % 36, b = bc / 36;
;     const int m0 = ck < 4 ? MLAT + b * TCTX + ck * 64 : b * TLAT + (ck - 4) * 64;
;     const int wave = tid >> 6, lane = tid & 63, dir = tid >> 8, t2 = tid & 255;
;     bf16_t* kn_s = (bf16_t*)sm;
;     bf16_t* qn_s = kn_s + 64 * 136;
;     float* KK = (float*)(sm + 34816);
;     float* QK = KK + 64 * 65;
;     float* gc_s = (float*)(sm + 68096);
;     float* be_s = gc_s + 128;
;     float* Ls = be_s + 128;
;     bf16_t* v_s = (bf16_t*)(sm + 101888);
;     {
;         const int r = tid >> 3, c16 = (tid & 7) * 16;
;         const bf16_t* ks = (const bf16_t*)(p.ws + WS_KN) + (size_t)(m0 + r) * 512 + h * 128 + c16;
;         const bf16_t* qs = (const bf16_t*)(p.ws + WS_QN) + (size_t)(m0 + r) * 512 + h * 128 + c16;
;         *(u32x4*)(kn_s + r * 136 + c16) = *(const u32x4*)ks; *(u32x4*)(kn_s + r * 136 + c16 + 8) = *(const u32x4*)(ks + 8);
;         *(u32x4*)(qn_s + r * 136 + c16) = *(const u32x4*)qs; *(u32x4*)(qn_s + r * 136 + c16 + 8) = *(const u32x4*)(qs + 8);
;         const bf16_t* vs = (const bf16_t*)(p.ws + WS_VV) + (size_t)(m0 + r) * 512 + h * 128 + c16;
;         *(u32x4*)(v_s + r * 136 + c16) = *(const u32x4*)vs; *(u32x4*)(v_s + r * 136 + c16 + 8) = *(const u32x4*)(vs + 8);
;     }
;     if (t2 < 64) {
;         const int tok = dir ? 63 - t2 : t2;
;         const float* gb = (const float*)(p.ws + WS_GB) + (size_t)(m0 + tok) * 16;
;         float gv = gb[dir * 4 + h]; const float bv = gb[8 + dir * 4 + h];
; #pragma unroll
;         for (int o = 1; o < 64; o <<= 1) { const float v = __shfl_up(gv, o); if (lane >= o) gv += v; }
;         gc_s[dir * 64 + t2] = gv; be_s[dir * 64 + t2] = bv;
;     }
;     __syncthreads();
;     {
;         const int which = wave >> 2, it = wave & 3, fr = lane & 15, g = lane >> 4;
;         const bf16_t* As = which ? qn_s : kn_s; float* Out = which ? QK : KK;
;         bf16x8 a[4];
; #pragma unroll
;         for (int ks = 0; ks < 4; ++ks) a[ks] = *(const bf16x8*)(As + (it * 16 + fr) * 136 + ks * 32 + g * 8);
; #pragma unroll
;         for (int jt = 0; jt < 4; ++jt) {
;             f32x4 acc = {0.f, 0.f, 0.f, 0.f};
; #pragma unroll
.LBB0_569:
	s_or_b64 exec, exec, s[2:3]
	v_readlane_b32 s2, v253, 62
	v_mov_b32_e32 v0, v1
	v_readlane_b32 s3, v253, 63
	s_waitcnt lgkmcnt(0)
	s_barrier
	s_andn2_b64 vcc, exec, s[2:3]
	v_readfirstlane_b32 s2, v0
	s_cbranch_vccnz .LBB0_665
	v_readlane_b32 s6, v254, 54
	v_readlane_b32 s7, v254, 55
	s_load_dwordx2 s[44:45], s[6:7], s2 offset:0xa8
	s_movk_i32 s1, 0xff
	v_cmp_lt_u32_e64 s[6:7], s1, v144
	v_lshlrev_b32_e32 v88, 4, v144
	v_ashrrev_i32_e32 v9, 3, v144
	s_waitcnt lgkmcnt(0)
	s_add_u32 s46, s44, 0x11300000
	s_addc_u32 s47, s45, 0
	s_add_u32 s48, s44, 0x10100000
	s_addc_u32 s49, s45, 0
	s_add_u32 s28, s44, 0x12500000
	s_addc_u32 s29, s45, 0
	v_writelane_b32 v255, s6, 10
	v_and_b32_e32 v2, 0x70, v88
	s_movk_i32 s3, 0x110
	v_writelane_b32 v255, s7, 11
	s_add_u32 s6, s44, 0xff00000
	v_mul_lo_u32 v0, v9, s3
	v_lshlrev_b32_e32 v3, 1, v2
	v_readlane_b32 s42, v254, 43
	s_addc_u32 s7, s45, 0
	v_add3_u32 v89, 0, v0, v3
	v_add3_u32 v90, s42, v0, v3
	v_and_b32_e32 v0, 63, v144
	v_writelane_b32 v255, s6, 14
	v_and_b32_e32 v8, 0xff, v144
	s_movk_i32 s2, 0x100
	v_writelane_b32 v255, s7, 15
	v_cmp_eq_u32_e64 s[6:7], 0, v0
	v_cmp_gt_u32_e32 vcc, s2, v144
	v_sub_u32_e32 v3, 63, v8
	v_writelane_b32 v255, s6, 16
	v_cndmask_b32_e32 v91, v3, v8, vcc
	v_and_b32_e32 v3, 0xffffff00, v144
	v_writelane_b32 v255, s7, 17
	v_cmp_gt_u32_e64 s[6:7], 2, v0
	v_lshlrev_b32_e32 v6, 2, v8
	v_readlane_b32 s1, v254, 44
	v_writelane_b32 v255, s6, 18
	v_readlane_b32 s50, v254, 45
	v_readlane_b32 s2, v254, 46
	v_writelane_b32 v255, s7, 19
	v_cmp_gt_u32_e64 s[6:7], 4, v0
	s_waitcnt vmcnt(1)
	v_mov_b32_e32 v5, s2
	v_lshrrev_b32_e32 v7, 2, v144
	v_writelane_b32 v255, s6, 20
	v_cndmask_b32_e64 v5, v5, 0, vcc
	v_readlane_b32 s2, v254, 48
	v_writelane_b32 v255, s7, 21
	v_cmp_gt_u32_e64 s[6:7], 8, v0
	v_bfe_u32 v22, v144, 2, 6
	v_ashrrev_i32_e32 v4, 8, v144
	v_writelane_b32 v255, s6, 22
	v_bitop3_b32 v14, v88, 62, 48 bitop3:0x6c
	v_bitop3_b32 v15, v88, 61, 48 bitop3:0x6c
	v_writelane_b32 v255, s7, 23
	v_cmp_gt_u32_e64 s[6:7], 16, v0
	v_bitop3_b32 v13, v88, 63, 48 bitop3:0x6c
	v_bitop3_b32 v20, v88, 60, 48 bitop3:0x6c
	v_writelane_b32 v255, s6, 24
	v_bitop3_b32 v23, v88, 59, 48 bitop3:0x6c
	v_bitop3_b32 v31, v88, 58, 48 bitop3:0x6c
	v_writelane_b32 v255, s7, 25
	v_cmp_gt_u32_e64 s[6:7], 32, v0
	v_or_b32_e32 v0, v3, v6
	v_add_u32_e32 v92, s1, v0
	v_add_u32_e32 v93, s50, v0
	v_and_b32_e32 v0, 15, v144
	v_and_or_b32 v11, v7, 48, v0
	v_mad_u32_u24 v24, v11, s3, v5
	v_mov_b32_e32 v5, s2
	v_readlane_b32 s2, v254, 47
	v_and_b32_e32 v7, 60, v7
	v_mul_u32_u24_e32 v29, 0x104, v7
	v_mov_b32_e32 v11, s2
	v_cndmask_b32_e32 v5, v5, v11, vcc
	v_readlane_b32 s2, v254, 49
	v_xor_b32_e32 v7, 63, v22
	v_writelane_b32 v255, s6, 26
	v_lshl_add_u32 v27, v0, 2, v5
	v_mul_u32_u24_e32 v28, 0x110, v0
	v_lshl_add_u32 v94, v4, 14, s2
	v_and_b32_e32 v0, 48, v88
	v_cndmask_b32_e32 v7, v7, v22, vcc
	s_movk_i32 s2, 0x104
	v_writelane_b32 v255, s7, 27
	v_lshlrev_b32_e32 v11, 8, v22
	v_mad_u32_u24 v12, v7, s2, 0
	v_cmp_gt_u32_e64 s[2:3], v22, v0
	v_lshlrev_b32_e32 v17, 2, v0
	v_add3_u32 v96, v94, v11, v17
	v_writelane_b32 v255, s2, 8
	v_or_b32_e32 v11, 1, v0
	v_or_b32_e32 v21, 4, v0
	v_writelane_b32 v255, s3, 9
	v_cmp_gt_u32_e64 s[2:3], v22, v11
	v_cndmask_b32_e32 v11, v14, v11, vcc
	v_or_b32_e32 v14, 2, v0
	v_writelane_b32 v255, s2, 28
	v_or_b32_e32 v30, 5, v0
	v_or_b32_e32 v32, 6, v0
	v_writelane_b32 v255, s3, 29
	v_cmp_gt_u32_e64 s[2:3], v22, v14
	v_cndmask_b32_e32 v14, v15, v14, vcc
	v_or_b32_e32 v15, 3, v0
	v_writelane_b32 v255, s2, 30
	v_or_b32_e32 v34, 7, v0
	v_or_b32_e32 v36, 8, v0
	v_writelane_b32 v255, s3, 31
	v_cmp_gt_u32_e64 s[2:3], v22, v15
	v_or_b32_e32 v38, 9, v0
	v_or_b32_e32 v40, 10, v0
	v_writelane_b32 v255, s2, 32
	v_or_b32_e32 v42, 11, v0
	v_or_b32_e32 v44, 12, v0
	v_writelane_b32 v255, s3, 33
	v_cmp_gt_u32_e64 s[2:3], v22, v21
	v_or_b32_e32 v46, 13, v0
	v_or_b32_e32 v48, 14, v0
	v_writelane_b32 v255, s2, 34
	v_bitop3_b32 v33, v88, 57, 48 bitop3:0x6c
	v_bitop3_b32 v35, v88, 56, 48 bitop3:0x6c
	v_writelane_b32 v255, s3, 35
	v_cmp_gt_u32_e64 s[2:3], v22, v30
	v_bitop3_b32 v37, v88, 55, 48 bitop3:0x6c
	v_bitop3_b32 v39, v88, 54, 48 bitop3:0x6c
	v_writelane_b32 v255, s2, 36
	v_bitop3_b32 v41, v88, 53, 48 bitop3:0x6c
	v_bitop3_b32 v43, v88, 52, 48 bitop3:0x6c
	v_writelane_b32 v255, s3, 37
	v_cmp_gt_u32_e64 s[2:3], v22, v32
	v_bitop3_b32 v45, v88, 51, 48 bitop3:0x6c
	v_bitop3_b32 v47, v88, 50, 48 bitop3:0x6c
	v_writelane_b32 v255, s2, 38
	v_bitop3_b32 v49, v88, 49, 48 bitop3:0x6c
	v_or_b32_e32 v50, 15, v0
	v_writelane_b32 v255, s3, 39
	v_cmp_gt_u32_e64 s[2:3], v22, v34
	v_bitop3_b32 v51, v88, 48, v88 bitop3:0xc
	v_cndmask_b32_e32 v13, v13, v0, vcc
	v_writelane_b32 v255, s2, 40
	v_cndmask_b32_e32 v15, v20, v15, vcc
	v_cndmask_b32_e32 v21, v23, v21, vcc
	v_writelane_b32 v255, s3, 41
	v_cmp_gt_u32_e64 s[2:3], v22, v36
	v_cndmask_b32_e32 v30, v31, v30, vcc
	v_cndmask_b32_e32 v32, v33, v32, vcc
	v_writelane_b32 v255, s2, 42
	v_cndmask_b32_e32 v34, v35, v34, vcc
	v_cndmask_b32_e32 v36, v37, v36, vcc
	v_writelane_b32 v255, s3, 43
	v_cmp_gt_u32_e64 s[2:3], v22, v38
	v_cndmask_b32_e32 v38, v39, v38, vcc
	v_cmp_gt_u32_e64 s[86:87], v22, v50
	v_writelane_b32 v255, s2, 44
; __device__ __forceinline__ void dn_prep_task(const P& p, int task, unsigned char* sm, int tid) {
;     ...
;     {
;         const int r = tid >> 3, c16 = (tid & 7) * 16;
;         const bf16_t* ks = (const bf16_t*)(p.ws + WS_KN) + (size_t)(m0 + r) * 512 + h * 128 + c16;
;         const bf16_t* qs = (const bf16_t*)(p.ws + WS_QN) + (size_t)(m0 + r) * 512 + h * 128 + c16;
;         *(u32x4*)(kn_s + r * 136 + c16) = *(const u32x4*)ks; *(u32x4*)(kn_s + r * 136 + c16 + 8) = *(const u32x4*)(ks + 8);
;         *(u32x4*)(qn_s + r * 136 + c16) = *(const u32x4*)qs; *(u32x4*)(qn_s + r * 136 + c16 + 8) = *(const u32x4*)(qs + 8);
;         const bf16_t* vs = (const bf16_t*)(p.ws + WS_VV) + (size_t)(m0 + r) * 512 + h * 128 + c16;
;         *(u32x4*)(v_s + r * 136 + c16) = *(const u32x4*)vs; *(u32x4*)(v_s + r * 136 + c16 + 8) = *(const u32x4*)(vs + 8);
;     }
;     if (t2 < 64) {
;         const int tok = dir ? 63 - t2 : t2;
;         const float* gb = (const float*)(p.ws + WS_GB) + (size_t)(m0 + tok) * 16;
;         float gv = gb[dir * 4 + h]; const float bv = gb[8 + dir * 4 + h];
; #pragma unroll
;         for (int o = 1; o < 64; o <<= 1) { const float v = __shfl_up(gv, o); if (lane >= o) gv += v; }
;         gc_s[dir * 64 + t2] = gv; be_s[dir * 64 + t2] = bv;
;     }
;     __syncthreads();
;     {
;         const int which = wave >> 2, it = wave & 3, fr = lane & 15, g = lane >> 4;
;         const bf16_t* As = which ? qn_s : kn_s; float* Out = which ? QK : KK;
;         bf16x8 a[4];
; #pragma unroll
;         for (int ks = 0; ks < 4; ++ks) a[ks] = *(const bf16x8*)(As + (it * 16 + fr) * 136 + ks * 32 + g * 8);
; #pragma unroll
;         for (int jt = 0; jt < 4; ++jt) {
;             f32x4 acc = {0.f, 0.f, 0.f, 0.f};
; #pragma unroll
;             for (int ks = 0; ks < 4; ++ks) { const bf16x8 bb = *(const bf16x8*)(kn_s + (jt * 16 + fr) * 136 + ks * 32 + g * 8); acc = mfma16(a[ks], bb, acc); }
; #pragma unroll
;             for (int r = 0; r < 4; ++r) Out[(it * 16 + 4 * g + r) * 65 + jt * 16 + fr] = acc[r];
;         }
;     }
;     __syncthreads();
;     const float* gc = gc_s + dir * 64; const float* be = be_s + dir * 64; float* L = Ls + dir * 4096;
;     const size_t dt = (size_t)task * 2 + dir;
;     {
;         const int cp = t2 >> 2, s0 = (t2 & 3) * 16; const int ctok = dir ? 63 - cp : cp; const float gcc = gc[cp], bec = be[cp];
; #pragma unroll
	v_cndmask_b32_e32 v50, v51, v50, vcc
	v_lshlrev_b32_e32 v16, 2, v13
	v_writelane_b32 v255, s3, 45
	v_cmp_gt_u32_e64 s[2:3], v22, v40
	v_cndmask_b32_e32 v40, v41, v40, vcc
	v_lshlrev_b32_e32 v18, 2, v11
	v_writelane_b32 v255, s2, 46
	v_lshlrev_b32_e32 v19, 2, v14
	v_lshlrev_b32_e32 v20, 2, v15
	v_writelane_b32 v255, s3, 47
	v_cmp_gt_u32_e64 s[2:3], v22, v42
	v_cndmask_b32_e32 v42, v43, v42, vcc
	v_lshlrev_b32_e32 v23, 2, v21
	v_writelane_b32 v255, s2, 48
	v_lshlrev_b32_e32 v31, 2, v30
	v_lshlrev_b32_e32 v33, 2, v32
	v_writelane_b32 v255, s3, 49
	v_cmp_gt_u32_e64 s[2:3], v22, v44
	v_cndmask_b32_e32 v44, v45, v44, vcc
	v_lshlrev_b32_e32 v35, 2, v34
	v_writelane_b32 v255, s2, 50
	v_lshlrev_b32_e32 v37, 2, v36
	v_lshlrev_b32_e32 v39, 2, v38
	v_writelane_b32 v255, s3, 51
	v_cmp_gt_u32_e64 s[2:3], v22, v46
	v_cndmask_b32_e32 v46, v47, v46, vcc
	v_lshlrev_b32_e32 v41, 2, v40
	v_writelane_b32 v255, s2, 52
	v_lshlrev_b32_e32 v43, 2, v42
	v_lshlrev_b32_e32 v45, 2, v44
	v_writelane_b32 v255, s3, 53
	v_cmp_gt_u32_e64 s[2:3], v22, v48
	v_cndmask_b32_e32 v48, v49, v48, vcc
	v_lshlrev_b32_e32 v47, 2, v46
	v_writelane_b32 v255, s2, 54
	v_lshlrev_b32_e32 v49, 2, v48
	v_lshlrev_b32_e32 v51, 2, v50
	v_writelane_b32 v255, s3, 55
	v_cmp_eq_u32_e64 s[2:3], 0, v8
	v_cmp_ge_u32_e64 s[8:9], v7, v32
	v_mul_u32_u24_e32 v32, 0x110, v0
	v_writelane_b32 v255, s2, 56
	v_lshlrev_b32_e32 v0, 1, v8
	v_readlane_b32 s76, v254, 28
	v_writelane_b32 v255, s3, 57
	s_movk_i32 s2, 0x80
	v_ashrrev_i32_e32 v5, 31, v4
	v_add_u32_e32 v95, v12, v16
	v_add_u32_e32 v97, v12, v18
	v_add_u32_e32 v98, v12, v19
	v_add_u32_e32 v99, v12, v20
	v_add_u32_e32 v100, v12, v23
	v_add_u32_e32 v101, v12, v31
	v_add_u32_e32 v102, v12, v33
	v_add_u32_e32 v103, v12, v35
	v_add_u32_e32 v104, v12, v37
	v_add_u32_e32 v105, v12, v39
	v_add_u32_e32 v106, v12, v41
	v_add_u32_e32 v107, v12, v43
	v_add_u32_e32 v108, v12, v45
	v_add_u32_e32 v109, v12, v47
	v_add_u32_e32 v110, v12, v49
	v_add_u32_e32 v111, v12, v51
	v_mul_u32_u24_e32 v12, 0x104, v22
	v_cmp_gt_u32_e64 s[30:31], s2, v8
	s_movk_i32 s2, 0x7f
	v_add_u32_e32 v113, 0, v0
	v_add_u32_e32 v115, s42, v0
	v_add_u32_e32 v116, v94, v0
	v_lshlrev_b32_e32 v0, 6, v144
	v_add_u32_e32 v119, s1, v3
	v_readlane_b32 s77, v254, 29
	v_readlane_b32 s72, v254, 38
	v_cmp_ge_u32_e64 s[88:89], v7, v13
	v_add3_u32 v112, 0, v12, v17
	v_cmp_ge_u32_e64 s[90:91], v7, v11
	v_cmp_ge_u32_e64 s[84:85], v7, v21
	v_ashrrev_i32_e32 v11, 2, v144
	v_cmp_lt_u32_e64 s[34:35], s2, v8
	v_add_u32_e32 v128, v119, v20
	v_lshl_add_u64 v[12:13], v[0:1], 1, s[76:77]
	v_and_b32_e32 v0, 3, v144
	v_readlane_b32 s2, v254, 32
	v_lshlrev_b64 v[20:21], 10, v[4:5]
	v_readlane_b32 s73, v254, 39
	v_lshlrev_b32_e32 v10, 2, v4
	v_cmp_ge_u32_e64 s[92:93], v7, v14
	v_cmp_ge_u32_e64 s[94:95], v7, v15
	v_cmp_ge_u32_e64 s[6:7], v7, v30
	v_cmp_ge_u32_e64 s[10:11], v7, v34
	v_cmp_ge_u32_e64 s[12:13], v7, v36
	v_cmp_ge_u32_e64 s[14:15], v7, v38
	v_cmp_ge_u32_e64 s[16:17], v7, v40
	v_cmp_ge_u32_e64 s[18:19], v7, v42
	v_cmp_ge_u32_e64 s[20:21], v7, v44
	v_cmp_ge_u32_e64 s[22:23], v7, v46
	v_cmp_ge_u32_e64 s[24:25], v7, v48
	v_cmp_ge_u32_e64 s[26:27], v7, v50
	v_lshlrev_b32_e32 v14, 6, v11
	v_lshl_add_u32 v124, v7, 2, v119
	v_add_u32_e32 v126, v119, v18
	v_add_u32_e32 v127, v119, v19
	v_lshlrev_b32_e32 v0, 5, v0
	v_readlane_b32 s3, v254, 33
	v_lshl_add_u64 v[18:19], s[72:73], 0, v[20:21]
	v_mov_b32_e32 v7, v1
	v_lshlrev_b64 v[4:5], 13, v[4:5]
	v_and_b32_e32 v25, 48, v144
	v_ashrrev_i32_e32 v15, 31, v14
	v_add_u32_e32 v123, v119, v17
	v_add_u32_e32 v125, v119, v16
	v_lshl_add_u64 v[16:17], s[2:3], 0, v[0:1]
	v_lshl_add_u64 v[18:19], v[18:19], 0, v[6:7]
	v_readlane_b32 s72, v254, 40
	v_lshl_add_u64 v[4:5], s[2:3], 0, v[4:5]
	v_lshlrev_b32_e32 v6, 7, v22
	v_add_u32_e32 v26, 0, v25
	v_lshl_add_u32 v30, v11, 1, 0
	s_add_u32 s42, s44, 0x7f00000
	v_add_u32_e32 v120, s50, v3
	v_and_b32_e32 v3, 0xfc, v144
	v_lshl_add_u64 v[14:15], v[14:15], 1, v[16:17]
	v_lshlrev_b32_e32 v16, 7, v8
	v_mov_b32_e32 v17, v1
	v_readlane_b32 s73, v254, 41
	v_lshl_add_u64 v[4:5], v[4:5], 0, v[6:7]
	v_cmp_gt_u32_e64 s[40:41], 64, v8
	v_add_u32_e32 v114, 0xffffff00, v113
	v_add_u32_e32 v117, 0xffffff00, v116
	s_addc_u32 s43, s45, 0
	v_lshlrev_b32_e32 v118, 4, v8
	v_add_u32_e32 v121, v119, v3
	v_add_u32_e32 v122, v120, v3
	v_add_u32_e32 v129, v119, v23
	v_add_u32_e32 v130, v119, v31
	v_add_u32_e32 v131, v119, v33
	v_add_u32_e32 v132, v119, v35
	v_add_u32_e32 v133, v119, v37
	v_add_u32_e32 v134, v119, v39
	v_add_u32_e32 v135, v119, v41
	v_add_u32_e32 v136, v119, v43
	v_add_u32_e32 v137, v119, v45
	v_add_u32_e32 v143, v119, v47
	v_add_u32_e32 v145, v119, v49
	v_add_u32_e32 v146, v119, v51
	v_lshl_add_u32 v147, v91, 2, v119
	v_ashrrev_i32_e32 v11, 31, v10
	v_lshl_add_u64 v[16:17], s[76:77], 0, v[16:17]
	v_lshl_add_u64 v[20:21], s[72:73], 0, v[20:21]
	v_lshl_add_u64 v[22:23], v[4:5], 0, v[0:1]
	v_lshlrev_b32_e32 v0, 1, v2
	v_add_u32_e32 v148, v24, v25
	v_add_u32_e32 v149, v26, v28
	v_add_u32_e32 v150, v27, v29
	v_add_u32_e32 v151, v30, v32
	v_lshlrev_b32_e32 v24, 4, v8
	v_readlane_b32 s2, v254, 56
	v_readlane_b32 s3, v254, 57
	s_branch .LBB0_573
	s_nop 0
	s_nop 0
	s_nop 0
	s_nop 0
	s_nop 0
	s_nop 0
	s_nop 0
